# v22 + counted vmcnt at first k-tile of the second gemm_res tile
# baseline (speedup 1.0000x reference)
;     ...
;     for (int kt = 0; kt < nk; ++kt) {
;         asm volatile("s_waitcnt vmcnt(0)\n\ts_barrier" ::: "memory");
;         if (kt + 1 < nk) issue(kt + 1, (kt + 1) & 1);
.LBB0_210:
	s_cmp_lg_u32 s43, 0
	s_cbranch_scc1 .Lgr10_fullw
	s_cmp_eq_u32 s22, 0
	s_cbranch_scc1 .Lgr10_fullw
	s_waitcnt vmcnt(16)
	s_branch .Lgr10_bar2

;     ...
;     for (int kt = 0; kt < nk; ++kt) {
;         asm volatile("s_waitcnt vmcnt(0)\n\ts_barrier" ::: "memory");
;         if (kt + 1 < nk) issue(kt + 1, (kt + 1) & 1);
.Lgr10_bar2:
	s_barrier
	s_cmp_lt_u32 s43, 15
	s_mov_b64 s[40:41], -1
	s_cbranch_scc1 .LBB0_212
	s_add_i32 s64, s47, 0x8000
	s_mov_b64 s[40:41], 0

;     ...
;     for (int kt = 0; kt < nk; ++kt) {
;         asm volatile("s_waitcnt vmcnt(0)\n\ts_barrier" ::: "memory");
;         if (kt + 1 < nk) issue(kt + 1, (kt + 1) & 1);
.LBB0_758:
	s_cmp_lg_u32 s64, 0
	s_cbranch_scc1 .Lgr28_fullw
	s_cmp_eq_u32 s6, 0
	s_cbranch_scc1 .Lgr28_fullw
	s_waitcnt vmcnt(16)
	s_branch .Lgr28_bar2

;     ...
;     for (int kt = 0; kt < nk; ++kt) {
;         asm volatile("s_waitcnt vmcnt(0)\n\ts_barrier" ::: "memory");
;         if (kt + 1 < nk) issue(kt + 1, (kt + 1) & 1);
.Lgr28_bar2:
	s_barrier
	s_cmp_lt_u32 s64, 43
	s_mov_b64 s[40:41], -1
	s_cbranch_scc1 .LBB0_760
	s_add_i32 s66, s65, 0x8000
	s_mov_b64 s[40:41], 0
